# xcd barrier instead of cg grid.sync after prep; GEMM accumulators zeroed with v_mov_b64
# speedup vs baseline: 1.0268x; 1.0068x over previous
; #define LAS __attribute__((address_space(3)))
; #define PREF const __attribute__((address_space(4))) Params&
; #define opaque_tid() opaque_tid_w(wid_u)
; __device__ __forceinline__ unsigned xb_ld(unsigned* p)              { return __hip_atomic_load(p, __ATOMIC_RELAXED, __HIP_MEMORY_SCOPE_AGENT); }
; __device__ __forceinline__ unsigned xb_add(unsigned* p, unsigned v) { return __hip_atomic_fetch_add(p, v, __ATOMIC_RELAXED, __HIP_MEMORY_SCOPE_AGENT); }
; __device__ __forceinline__ unsigned xb_xcc_id() { return (unsigned)__builtin_amdgcn_s_getreg((3 << 11) | 20) & 0xFu; }
; __device__ __forceinline__ void xcd_barrier_complete(unsigned* bar, unsigned x, unsigned& nloc, unsigned& nx) {
;   const unsigned G = gridDim.x * gridDim.y * gridDim.z;
;   unsigned sum, cnt, mine, sp = 0u;
;   for (;;) {
;     sum = 0u; cnt = 0u; mine = 0u;
; #pragma unroll
;     for (unsigned j = 0; j < 16; ++j) { const unsigned c = xb_ld(&bar[XB_XCNT(j)]); sum += c; cnt += (c > 0u) ? 1u : 0u; mine = (j == x) ? c : mine; }
; __device__ __forceinline__ void xcd_barrier(PREF p, volatile LAS unsigned* st_, const int wid_u) {
;   asm volatile("s_waitcnt vmcnt(0)" ::: "memory");
;   __syncthreads();
;   if (opaque_tid() == 0) {
;     XcdBarrier b; b.bar = (unsigned*)(p.ws + OFF_BAR); b.x = xb_xcc_id(); b.st = st_;
;     unsigned* bar = b.bar;
;     __builtin_amdgcn_s_waitcnt(0);
;     unsigned nloc = b.st[0], nx = b.st[1];
;     if (nloc == 0u) { xcd_barrier_complete(bar, b.x, nloc, nx); b.st[0] = nloc; b.st[1] = nx; }
;     const unsigned old = xb_add(&bar[XB_XSUB(b.x)], 1u);
.LBB0_67:
	s_load_dwordx2 s[2:3], s[0:1], 0x110
	s_waitcnt vmcnt(0)
	s_waitcnt lgkmcnt(0)
	s_lshl_b32 s4, s66, 6
	s_sub_i32 s58, 0, s4
	s_barrier
	v_mbcnt_lo_u32_b32 v0, -1, 0
	v_mbcnt_hi_u32_b32 v0, -1, v0
	s_nop 0
	v_cmp_eq_u32_e32 vcc, s58, v0
	s_and_saveexec_b64 s[4:5], vcc
	s_cbranch_execz .Lgs_138
	s_add_i32 s7, 0, 0x27a00
	v_mov_b32_e32 v0, s7
	s_getreg_b32 s6, hwreg(HW_REG_XCC_ID, 0, 4)
	s_waitcnt vmcnt(0) expcnt(0) lgkmcnt(0)
	ds_read_b32 v2, v0
	s_add_i32 s7, 0, 0x27a04
	v_mov_b32_e32 v0, s7
	ds_read_b32 v0, v0
	s_and_b32 s50, s6, 15
	s_waitcnt lgkmcnt(1)
	v_cmp_ne_u32_e32 vcc, 0, v2
	s_cbranch_vccnz .Lgs_102
	s_add_u32 s6, s2, 0x3ee90200
	s_addc_u32 s7, s3, 0
	s_add_u32 s8, s2, 0x3ee90400
	s_addc_u32 s9, s3, 0
	s_add_u32 s10, s2, 0x3ee90500
	s_addc_u32 s11, s3, 0
	s_add_u32 s12, s2, 0x3ee90600
	s_addc_u32 s13, s3, 0
	s_add_u32 s14, s2, 0x3ee90700
	s_addc_u32 s15, s3, 0
	s_add_u32 s16, s2, 0x3ee90800
	s_addc_u32 s17, s3, 0
	s_add_u32 s18, s2, 0x3ee90900
	s_addc_u32 s19, s3, 0
	s_add_u32 s20, s2, 0x3ee90a00
	s_addc_u32 s21, s3, 0
	s_add_u32 s22, s2, 0x3ee90b00
	s_addc_u32 s23, s3, 0
	s_add_u32 s24, s2, 0x3ee90c00
	s_addc_u32 s25, s3, 0
	s_add_u32 s26, s2, 0x3ee90d00
	s_addc_u32 s27, s3, 0
	s_add_u32 s28, s2, 0x3ee90e00
	s_addc_u32 s29, s3, 0
	s_add_u32 s30, s2, 0x3ee90f00
	s_addc_u32 s31, s3, 0
	s_add_u32 s34, s2, 0x3ee91000
	s_addc_u32 s35, s3, 0
	s_add_u32 s36, s2, 0x3ee91100
	s_addc_u32 s37, s3, 0
	s_add_u32 s38, s2, 0x3ee91200
	s_addc_u32 s39, s3, 0
	s_mul_i32 s51, s43, s85
	s_add_u32 s40, s2, 0x3ee91300
	s_mul_i32 s51, s51, s42
	s_addc_u32 s41, s3, 0
	s_mov_b32 s52, 1
	v_mov_b32_e32 v16, 0
	s_branch .Lgs_90

; #define opaque_tid() opaque_tid_w(wid_u)
; template <int MODE> ...
;   const int tid_ = opaque_tid();
;   const int lane = tid_ & 63;
;   const int gw = blockIdx.x * 8 + (tid_ >> 6), GW = gridDim.x * 8;
;   for (int chunk = gw; chunk < NTOK / 16; chunk += GW) {
;     const int row0 = chunk * 16;
;     int s, t, T;
;     row_seq(row0, s, t, T);
;     const float* md = mod + s * 9216;
;     f32x4 Am[4], Bm[4], Gm[4];
; #pragma unroll
;     for (int i = 0; i < 4; ++i) {
;       const int c = i * 256 + lane * 4;
;       if (MODE != 2) {
;         f32x4 np = *(const f32x4*)(npre + c), sc = *(const f32x4*)(md + (shift_idx + 1) * 1024 + c);
;         Am[i] = np * (sc + 1.f);
;         Bm[i] = *(const f32x4*)(md + shift_idx * 1024 + c);
;       }
;       if (MODE != 0) {
;         f32x4 g = *(const f32x4*)(md + gate_idx * 1024 + c), po = *(const f32x4*)(npost + c);
;         Gm[i] = g * po * cgate;
;       }
;     }
.Lgs_138:
	s_or_b64 exec, exec, s[4:5]
	s_mov_b64 s[10:11], s[0:1]
	s_barrier
	s_load_dwordx2 s[2:3], s[10:11], 0x110
	v_mbcnt_lo_u32_b32 v0, -1, 0
	v_mbcnt_hi_u32_b32 v0, -1, v0
	s_lshl_b32 s57, s33, 3
	v_add_u32_e32 v1, s84, v0
	v_ashrrev_i32_e32 v16, 6, v1
	v_add_u32_e32 v62, s57, v16
	s_movk_i32 s4, 0x1800
	s_lshl_b32 s86, s42, 3
	v_cmp_gt_i32_e32 vcc, s4, v62
	s_and_saveexec_b64 s[8:9], vcc
	s_cbranch_execz .LBB0_86
	s_load_dwordx2 s[4:5], s[10:11], 0x30
	v_lshlrev_b32_e32 v0, 2, v0
	v_and_b32_e32 v18, 0xfc, v0
	v_lshlrev_b32_e32 v17, 2, v18
	v_mov_b32_e32 v33, 0
	s_waitcnt lgkmcnt(0)
	global_load_dwordx4 v[0:3], v17, s[4:5]
	global_load_dwordx4 v[4:7], v17, s[4:5] offset:1024
	global_load_dwordx4 v[8:11], v17, s[4:5] offset:2048
	global_load_dwordx4 v[12:15], v17, s[4:5] offset:3072
	s_load_dwordx4 s[4:7], s[10:11], 0x0
	v_lshlrev_b32_e32 v32, 1, v18
	v_lshl_add_u64 v[20:21], s[2:3], 0, v[32:33]
	s_mov_b64 s[12:13], 0x2e90000
	s_add_u32 s10, s2, 0x2800000
	v_lshl_add_u64 v[34:35], v[20:21], 0, s[12:13]
	v_or_b32_e32 v20, 0x100, v18
	v_or_b32_e32 v22, 0x200, v18
	v_or_b32_e32 v24, 0x300, v18
	v_lshlrev_b32_e32 v16, 4, v16
	s_addc_u32 s11, s3, 0
	v_lshl_add_u32 v63, s33, 7, v16
	s_lshl_b32 s18, s42, 7
	s_mov_b64 s[12:13], 0
	s_movk_i32 s19, 0x800
	v_mov_b32_e32 v64, 0xffff8000
	s_mov_b64 s[14:15], 0x1000
	v_lshlrev_b32_e32 v32, 2, v18
	v_lshlrev_b32_e32 v36, 2, v20
	v_mov_b32_e32 v37, v33
	v_lshlrev_b32_e32 v38, 2, v22
	v_mov_b32_e32 v39, v33
	v_lshlrev_b32_e32 v40, 2, v24
	v_mov_b32_e32 v41, v33
	s_movk_i32 s20, 0x7fff
	v_mov_b32_e32 v65, 0x358637bd
	s_mov_b32 s21, 0x800000
	s_movk_i32 s22, 0x17ff
	s_branch .LBB0_80

; __device__ __forceinline__ void gemm_phase(const bf16_t* __restrict__ A, const bf16_t* __restrict__ Bt, bf16_t* __restrict__ C, int M, int N, int K,
;                                            int ldc, const int EPI, char* smem, const int wid_u) {
;     ...
;     const bool has_next = gemm_unit(ui + 1, nM, nN, nwg, npm, npn);
;     const char* nA = has_next ? (const char*)A + (size_t)npm * tstep : cA;
;     const char* nB = has_next ? (const char*)Bt + (size_t)npn * tstep : cB;
;     for (int t = 0; t < nt; t += 2) {
;       const bool last = (t == nt - 2);
;       const char* a1 = cA + (size_t)(t + 1) * kstep;
;       const char* a2 = last ? nA : cA + (size_t)(t + 2) * kstep;
;       const char* b2 = last ? nB : cB + (size_t)(t + 2) * kstep;
;     ...
; #pragma unroll
;     for (int a = 0; a < 2; ++a)
; #pragma unroll
;       for (int b = 0; b < 2; ++b)
; #pragma unroll
;         for (int m = 0; m < 4; ++m)
; #pragma unroll
;           for (int n = 0; n < 2; ++n) acc[a][b][m][n] = (f32x4){0.f, 0.f, 0.f, 0.f};
;     pm = npm; pn = npn; cA = nA; cB = nB; ++ui;
.LBB0_144:
	v_cmp_lt_u64_e32 vcc, s[12:13], v[138:139]
	s_lshl_b64 s[12:13], s[8:9], 19
	s_add_u32 s12, s25, s12
	s_addc_u32 s13, s26, s13
	s_and_b64 s[14:15], vcc, exec
	s_mov_b32 s11, s9
	s_cselect_b32 s44, s13, s17
	s_cselect_b32 s45, s12, s16
	s_lshl_b64 s[14:15], s[10:11], 19
	s_add_u32 s14, s4, s14
	s_addc_u32 s15, s5, s15
	s_and_b64 s[20:21], vcc, exec
	s_cselect_b32 s11, s15, s19
	s_cselect_b32 s46, s14, s18
	s_add_u32 s47, s18, 0x100
	v_mov_b64_e32 v[0:1], 0
	v_mov_b64_e32 v[2:3], 0
	v_mov_b64_e32 v[4:5], 0
	v_mov_b64_e32 v[6:7], 0
	v_mov_b64_e32 v[8:9], 0
	v_mov_b64_e32 v[10:11], 0
	v_mov_b64_e32 v[12:13], 0
	v_mov_b64_e32 v[14:15], 0
	v_mov_b64_e32 v[16:17], 0
	v_mov_b64_e32 v[18:19], 0
	v_mov_b64_e32 v[20:21], 0
	v_mov_b64_e32 v[22:23], 0
	v_mov_b64_e32 v[24:25], 0
	v_mov_b64_e32 v[26:27], 0
	v_mov_b64_e32 v[28:29], 0
	v_mov_b64_e32 v[30:31], 0
	v_mov_b64_e32 v[32:33], 0
	v_mov_b64_e32 v[34:35], 0
	v_mov_b64_e32 v[36:37], 0
	v_mov_b64_e32 v[38:39], 0
	v_mov_b64_e32 v[40:41], 0
	v_mov_b64_e32 v[42:43], 0
	v_mov_b64_e32 v[44:45], 0
	v_mov_b64_e32 v[46:47], 0
	v_mov_b64_e32 v[48:49], 0
	v_mov_b64_e32 v[50:51], 0
	v_mov_b64_e32 v[52:53], 0
	v_mov_b64_e32 v[54:55], 0
	v_mov_b64_e32 v[56:57], 0
	v_mov_b64_e32 v[58:59], 0
	v_mov_b64_e32 v[60:61], 0
	v_mov_b64_e32 v[62:63], 0
	v_mov_b64_e32 v[64:65], 0
	v_mov_b64_e32 v[66:67], 0
	v_mov_b64_e32 v[68:69], 0
	v_mov_b64_e32 v[70:71], 0
	v_mov_b64_e32 v[72:73], 0
	v_mov_b64_e32 v[74:75], 0
	v_mov_b64_e32 v[76:77], 0
	v_mov_b64_e32 v[78:79], 0
	v_mov_b64_e32 v[80:81], 0
	v_mov_b64_e32 v[82:83], 0
	v_mov_b64_e32 v[84:85], 0
	v_mov_b64_e32 v[86:87], 0
	v_mov_b64_e32 v[88:89], 0
	v_mov_b64_e32 v[90:91], 0
	v_mov_b64_e32 v[92:93], 0
	v_mov_b64_e32 v[94:95], 0
	v_mov_b64_e32 v[96:97], 0
	v_mov_b64_e32 v[98:99], 0
	v_mov_b64_e32 v[100:101], 0
	v_mov_b64_e32 v[102:103], 0
	v_mov_b64_e32 v[104:105], 0
	v_mov_b64_e32 v[106:107], 0
	v_mov_b64_e32 v[108:109], 0
	v_mov_b64_e32 v[110:111], 0
	v_mov_b64_e32 v[112:113], 0
	v_mov_b64_e32 v[114:115], 0
	v_mov_b64_e32 v[116:117], 0
	v_mov_b64_e32 v[118:119], 0
	v_mov_b64_e32 v[120:121], 0
	v_mov_b64_e32 v[122:123], 0
	v_mov_b64_e32 v[124:125], 0
	v_mov_b64_e32 v[126:127], 0
	s_addc_u32 s48, s19, 0
	s_mov_b32 s49, -2

; __device__ __forceinline__ void gemm_phase(const bf16_t* __restrict__ A, const bf16_t* __restrict__ Bt, bf16_t* __restrict__ C, int M, int N, int K,
;                                            int ldc, const int EPI, char* smem, const int wid_u) {
;     ...
; #pragma unroll
;     for (int a = 0; a < 2; ++a)
; #pragma unroll
;       for (int b = 0; b < 2; ++b)
; #pragma unroll
;         for (int m = 0; m < 4; ++m)
; #pragma unroll
;           for (int n = 0; n < 2; ++n) acc[a][b][m][n] = (f32x4){0.f, 0.f, 0.f, 0.f};
;     pm = npm; pn = npn; cA = nA; cB = nB; ++ui;
.LBB0_212:
	s_add_u32 s51, s16, 0x100
	v_mov_b64_e32 v[0:1], 0
	v_mov_b64_e32 v[2:3], 0
	v_mov_b64_e32 v[4:5], 0
	v_mov_b64_e32 v[6:7], 0
	v_mov_b64_e32 v[8:9], 0
	v_mov_b64_e32 v[10:11], 0
	v_mov_b64_e32 v[12:13], 0
	v_mov_b64_e32 v[14:15], 0
	v_mov_b64_e32 v[16:17], 0
	v_mov_b64_e32 v[18:19], 0
	v_mov_b64_e32 v[20:21], 0
	v_mov_b64_e32 v[22:23], 0
	v_mov_b64_e32 v[24:25], 0
	v_mov_b64_e32 v[26:27], 0
	v_mov_b64_e32 v[28:29], 0
	v_mov_b64_e32 v[30:31], 0
	v_mov_b64_e32 v[32:33], 0
	v_mov_b64_e32 v[34:35], 0
	v_mov_b64_e32 v[36:37], 0
	v_mov_b64_e32 v[38:39], 0
	v_mov_b64_e32 v[40:41], 0
	v_mov_b64_e32 v[42:43], 0
	v_mov_b64_e32 v[44:45], 0
	v_mov_b64_e32 v[46:47], 0
	v_mov_b64_e32 v[48:49], 0
	v_mov_b64_e32 v[50:51], 0
	v_mov_b64_e32 v[52:53], 0
	v_mov_b64_e32 v[54:55], 0
	v_mov_b64_e32 v[56:57], 0
	v_mov_b64_e32 v[58:59], 0
	v_mov_b64_e32 v[60:61], 0
	v_mov_b64_e32 v[62:63], 0
	v_mov_b64_e32 v[64:65], 0
	v_mov_b64_e32 v[66:67], 0
	v_mov_b64_e32 v[68:69], 0
	v_mov_b64_e32 v[70:71], 0
	v_mov_b64_e32 v[72:73], 0
	v_mov_b64_e32 v[74:75], 0
	v_mov_b64_e32 v[76:77], 0
	v_mov_b64_e32 v[78:79], 0
	v_mov_b64_e32 v[80:81], 0
	v_mov_b64_e32 v[82:83], 0
	v_mov_b64_e32 v[84:85], 0
	v_mov_b64_e32 v[86:87], 0
	v_mov_b64_e32 v[88:89], 0
	v_mov_b64_e32 v[90:91], 0
	v_mov_b64_e32 v[92:93], 0
	v_mov_b64_e32 v[94:95], 0
	v_mov_b64_e32 v[96:97], 0
	v_mov_b64_e32 v[98:99], 0
	v_mov_b64_e32 v[100:101], 0
	v_mov_b64_e32 v[102:103], 0
	v_mov_b64_e32 v[104:105], 0
	v_mov_b64_e32 v[106:107], 0
	v_mov_b64_e32 v[108:109], 0
	v_mov_b64_e32 v[110:111], 0
	v_mov_b64_e32 v[112:113], 0
	v_mov_b64_e32 v[114:115], 0
	v_mov_b64_e32 v[116:117], 0
	v_mov_b64_e32 v[118:119], 0
	v_mov_b64_e32 v[120:121], 0
	v_mov_b64_e32 v[122:123], 0
	v_mov_b64_e32 v[124:125], 0
	v_mov_b64_e32 v[126:127], 0
	s_addc_u32 s52, s17, 0
	s_mov_b32 s53, -2

; __device__ __forceinline__ void gemm_phase(const bf16_t* __restrict__ A, const bf16_t* __restrict__ Bt, bf16_t* __restrict__ C, int M, int N, int K,
;                                            int ldc, const int EPI, char* smem, const int wid_u) {
;     ...
;     const bool has_next = gemm_unit(ui + 1, nM, nN, nwg, npm, npn);
;     const char* nA = has_next ? (const char*)A + (size_t)npm * tstep : cA;
;     const char* nB = has_next ? (const char*)Bt + (size_t)npn * tstep : cB;
;     for (int t = 0; t < nt; t += 2) {
;       const bool last = (t == nt - 2);
;       const char* a1 = cA + (size_t)(t + 1) * kstep;
;       const char* a2 = last ? nA : cA + (size_t)(t + 2) * kstep;
;       const char* b2 = last ? nB : cB + (size_t)(t + 2) * kstep;
;     ...
; #pragma unroll
;     for (int a = 0; a < 2; ++a)
; #pragma unroll
;       for (int b = 0; b < 2; ++b)
; #pragma unroll
;         for (int m = 0; m < 4; ++m)
; #pragma unroll
;           for (int n = 0; n < 2; ++n) acc[a][b][m][n] = (f32x4){0.f, 0.f, 0.f, 0.f};
;     pm = npm; pn = npn; cA = nA; cB = nB; ++ui;
.LBB0_333:
	v_cmp_lt_u64_e32 vcc, s[12:13], v[138:139]
	s_lshl_b64 s[12:13], s[6:7], 19
	s_add_u32 s12, s25, s12
	s_addc_u32 s13, s26, s13
	s_and_b64 s[14:15], vcc, exec
	s_mov_b32 s11, s7
	s_cselect_b32 s46, s13, s17
	s_cselect_b32 s47, s12, s16
	s_lshl_b64 s[14:15], s[10:11], 19
	s_add_u32 s14, s27, s14
	s_addc_u32 s15, s28, s15
	s_and_b64 s[20:21], vcc, exec
	s_cselect_b32 s11, s15, s19
	s_cselect_b32 s48, s14, s18
	s_add_u32 s49, s18, 0x100
	v_mov_b64_e32 v[0:1], 0
	v_mov_b64_e32 v[2:3], 0
	v_mov_b64_e32 v[4:5], 0
	v_mov_b64_e32 v[6:7], 0
	v_mov_b64_e32 v[8:9], 0
	v_mov_b64_e32 v[10:11], 0
	v_mov_b64_e32 v[12:13], 0
	v_mov_b64_e32 v[14:15], 0
	v_mov_b64_e32 v[16:17], 0
	v_mov_b64_e32 v[18:19], 0
	v_mov_b64_e32 v[20:21], 0
	v_mov_b64_e32 v[22:23], 0
	v_mov_b64_e32 v[24:25], 0
	v_mov_b64_e32 v[26:27], 0
	v_mov_b64_e32 v[28:29], 0
	v_mov_b64_e32 v[30:31], 0
	v_mov_b64_e32 v[32:33], 0
	v_mov_b64_e32 v[34:35], 0
	v_mov_b64_e32 v[36:37], 0
	v_mov_b64_e32 v[38:39], 0
	v_mov_b64_e32 v[40:41], 0
	v_mov_b64_e32 v[42:43], 0
	v_mov_b64_e32 v[44:45], 0
	v_mov_b64_e32 v[46:47], 0
	v_mov_b64_e32 v[48:49], 0
	v_mov_b64_e32 v[50:51], 0
	v_mov_b64_e32 v[52:53], 0
	v_mov_b64_e32 v[54:55], 0
	v_mov_b64_e32 v[56:57], 0
	v_mov_b64_e32 v[58:59], 0
	v_mov_b64_e32 v[60:61], 0
	v_mov_b64_e32 v[62:63], 0
	v_mov_b64_e32 v[64:65], 0
	v_mov_b64_e32 v[66:67], 0
	v_mov_b64_e32 v[68:69], 0
	v_mov_b64_e32 v[70:71], 0
	v_mov_b64_e32 v[72:73], 0
	v_mov_b64_e32 v[74:75], 0
	v_mov_b64_e32 v[76:77], 0
	v_mov_b64_e32 v[78:79], 0
	v_mov_b64_e32 v[80:81], 0
	v_mov_b64_e32 v[82:83], 0
	v_mov_b64_e32 v[84:85], 0
	v_mov_b64_e32 v[86:87], 0
	v_mov_b64_e32 v[88:89], 0
	v_mov_b64_e32 v[90:91], 0
	v_mov_b64_e32 v[92:93], 0
	v_mov_b64_e32 v[94:95], 0
	v_mov_b64_e32 v[96:97], 0
	v_mov_b64_e32 v[98:99], 0
	v_mov_b64_e32 v[100:101], 0
	v_mov_b64_e32 v[102:103], 0
	v_mov_b64_e32 v[104:105], 0
	v_mov_b64_e32 v[106:107], 0
	v_mov_b64_e32 v[108:109], 0
	v_mov_b64_e32 v[110:111], 0
	v_mov_b64_e32 v[112:113], 0
	v_mov_b64_e32 v[114:115], 0
	v_mov_b64_e32 v[116:117], 0
	v_mov_b64_e32 v[118:119], 0
	v_mov_b64_e32 v[120:121], 0
	v_mov_b64_e32 v[122:123], 0
	v_mov_b64_e32 v[124:125], 0
	v_mov_b64_e32 v[126:127], 0
	s_addc_u32 s50, s19, 0
	s_mov_b32 s51, -2

; __device__ __forceinline__ void gemm_phase(const bf16_t* __restrict__ A, const bf16_t* __restrict__ Bt, bf16_t* __restrict__ C, int M, int N, int K,
;                                            int ldc, const int EPI, char* smem, const int wid_u) {
;     ...
;     const bool has_next = gemm_unit(ui + 1, nM, nN, nwg, npm, npn);
;     const char* nA = has_next ? (const char*)A + (size_t)npm * tstep : cA;
;     const char* nB = has_next ? (const char*)Bt + (size_t)npn * tstep : cB;
;     for (int t = 0; t < nt; t += 2) {
;       const bool last = (t == nt - 2);
;       const char* a1 = cA + (size_t)(t + 1) * kstep;
;       const char* a2 = last ? nA : cA + (size_t)(t + 2) * kstep;
;       const char* b2 = last ? nB : cB + (size_t)(t + 2) * kstep;
;     ...
; #pragma unroll
;     for (int a = 0; a < 2; ++a)
; #pragma unroll
;       for (int b = 0; b < 2; ++b)
; #pragma unroll
;         for (int m = 0; m < 4; ++m)
; #pragma unroll
;           for (int n = 0; n < 2; ++n) acc[a][b][m][n] = (f32x4){0.f, 0.f, 0.f, 0.f};
;     pm = npm; pn = npn; cA = nA; cB = nB; ++ui;
.LBB0_904:
	v_cmp_lt_u64_e32 vcc, s[12:13], v[138:139]
	s_lshl_b64 s[12:13], s[8:9], 19
	s_add_u32 s12, s25, s12
	s_addc_u32 s13, s26, s13
	s_and_b64 s[14:15], vcc, exec
	s_cselect_b32 s49, s13, s17
	s_cselect_b32 s50, s12, s16
	s_lshl_b32 s14, s46, 19
	s_add_u32 s14, s27, s14
	s_addc_u32 s15, s28, 0
	s_and_b64 s[20:21], vcc, exec
	s_cselect_b32 s51, s15, s19
	s_cselect_b32 s52, s14, s18
	s_add_u32 s53, s18, 0x100
	v_mov_b64_e32 v[0:1], 0
	v_mov_b64_e32 v[2:3], 0
	v_mov_b64_e32 v[4:5], 0
	v_mov_b64_e32 v[6:7], 0
	v_mov_b64_e32 v[8:9], 0
	v_mov_b64_e32 v[10:11], 0
	v_mov_b64_e32 v[12:13], 0
	v_mov_b64_e32 v[14:15], 0
	v_mov_b64_e32 v[16:17], 0
	v_mov_b64_e32 v[18:19], 0
	v_mov_b64_e32 v[20:21], 0
	v_mov_b64_e32 v[22:23], 0
	v_mov_b64_e32 v[24:25], 0
	v_mov_b64_e32 v[26:27], 0
	v_mov_b64_e32 v[28:29], 0
	v_mov_b64_e32 v[30:31], 0
	v_mov_b64_e32 v[32:33], 0
	v_mov_b64_e32 v[34:35], 0
	v_mov_b64_e32 v[36:37], 0
	v_mov_b64_e32 v[38:39], 0
	v_mov_b64_e32 v[40:41], 0
	v_mov_b64_e32 v[42:43], 0
	v_mov_b64_e32 v[44:45], 0
	v_mov_b64_e32 v[46:47], 0
	v_mov_b64_e32 v[48:49], 0
	v_mov_b64_e32 v[50:51], 0
	v_mov_b64_e32 v[52:53], 0
	v_mov_b64_e32 v[54:55], 0
	v_mov_b64_e32 v[56:57], 0
	v_mov_b64_e32 v[58:59], 0
	v_mov_b64_e32 v[60:61], 0
	v_mov_b64_e32 v[62:63], 0
	v_mov_b64_e32 v[64:65], 0
	v_mov_b64_e32 v[66:67], 0
	v_mov_b64_e32 v[68:69], 0
	v_mov_b64_e32 v[70:71], 0
	v_mov_b64_e32 v[72:73], 0
	v_mov_b64_e32 v[74:75], 0
	v_mov_b64_e32 v[76:77], 0
	v_mov_b64_e32 v[78:79], 0
	v_mov_b64_e32 v[80:81], 0
	v_mov_b64_e32 v[82:83], 0
	v_mov_b64_e32 v[84:85], 0
	v_mov_b64_e32 v[86:87], 0
	v_mov_b64_e32 v[88:89], 0
	v_mov_b64_e32 v[90:91], 0
	v_mov_b64_e32 v[92:93], 0
	v_mov_b64_e32 v[94:95], 0
	v_mov_b64_e32 v[96:97], 0
	v_mov_b64_e32 v[98:99], 0
	v_mov_b64_e32 v[100:101], 0
	v_mov_b64_e32 v[102:103], 0
	v_mov_b64_e32 v[104:105], 0
	v_mov_b64_e32 v[106:107], 0
	v_mov_b64_e32 v[108:109], 0
	v_mov_b64_e32 v[110:111], 0
	v_mov_b64_e32 v[112:113], 0
	v_mov_b64_e32 v[114:115], 0
	v_mov_b64_e32 v[116:117], 0
	v_mov_b64_e32 v[118:119], 0
	v_mov_b64_e32 v[120:121], 0
	v_mov_b64_e32 v[122:123], 0
	v_mov_b64_e32 v[124:125], 0
	v_mov_b64_e32 v[126:127], 0
	s_addc_u32 s54, s19, 0
	s_mov_b32 s55, -2

; __device__ __forceinline__ void gemm_phase(const bf16_t* __restrict__ A, const bf16_t* __restrict__ Bt, bf16_t* __restrict__ C, int M, int N, int K,
;                                            int ldc, const int EPI, char* smem, const int wid_u) {
;     ...
;     const bool has_next = gemm_unit(ui + 1, nM, nN, nwg, npm, npn);
;     const char* nA = has_next ? (const char*)A + (size_t)npm * tstep : cA;
;     const char* nB = has_next ? (const char*)Bt + (size_t)npn * tstep : cB;
;     for (int t = 0; t < nt; t += 2) {
;       const bool last = (t == nt - 2);
;       const char* a1 = cA + (size_t)(t + 1) * kstep;
;       const char* a2 = last ? nA : cA + (size_t)(t + 2) * kstep;
;       const char* b2 = last ? nB : cB + (size_t)(t + 2) * kstep;
;     ...
; #pragma unroll
;     for (int a = 0; a < 2; ++a)
; #pragma unroll
;       for (int b = 0; b < 2; ++b)
; #pragma unroll
;         for (int m = 0; m < 4; ++m)
; #pragma unroll
;           for (int n = 0; n < 2; ++n) acc[a][b][m][n] = (f32x4){0.f, 0.f, 0.f, 0.f};
;     pm = npm; pn = npn; cA = nA; cB = nB; ++ui;
.LBB0_1025:
	v_cmp_lt_u64_e32 vcc, s[14:15], v[138:139]
	s_lshl_b64 s[14:15], s[8:9], 19
	s_add_u32 s14, s27, s14
	s_addc_u32 s15, s28, s15
	s_and_b64 s[16:17], vcc, exec
	s_mov_b32 s13, s9
	s_cselect_b32 s48, s15, s19
	s_cselect_b32 s49, s14, s18
	s_lshl_b64 s[16:17], s[12:13], 19
	s_add_u32 s16, s29, s16
	s_addc_u32 s17, s30, s17
	s_and_b64 s[22:23], vcc, exec
	s_cselect_b32 s13, s17, s21
	s_cselect_b32 s50, s16, s20
	s_add_u32 s51, s20, 0x100
	v_mov_b64_e32 v[0:1], 0
	v_mov_b64_e32 v[2:3], 0
	v_mov_b64_e32 v[4:5], 0
	v_mov_b64_e32 v[6:7], 0
	v_mov_b64_e32 v[8:9], 0
	v_mov_b64_e32 v[10:11], 0
	v_mov_b64_e32 v[12:13], 0
	v_mov_b64_e32 v[14:15], 0
	v_mov_b64_e32 v[16:17], 0
	v_mov_b64_e32 v[18:19], 0
	v_mov_b64_e32 v[20:21], 0
	v_mov_b64_e32 v[22:23], 0
	v_mov_b64_e32 v[24:25], 0
	v_mov_b64_e32 v[26:27], 0
	v_mov_b64_e32 v[28:29], 0
	v_mov_b64_e32 v[30:31], 0
	v_mov_b64_e32 v[32:33], 0
	v_mov_b64_e32 v[34:35], 0
	v_mov_b64_e32 v[36:37], 0
	v_mov_b64_e32 v[38:39], 0
	v_mov_b64_e32 v[40:41], 0
	v_mov_b64_e32 v[42:43], 0
	v_mov_b64_e32 v[44:45], 0
	v_mov_b64_e32 v[46:47], 0
	v_mov_b64_e32 v[48:49], 0
	v_mov_b64_e32 v[50:51], 0
	v_mov_b64_e32 v[52:53], 0
	v_mov_b64_e32 v[54:55], 0
	v_mov_b64_e32 v[56:57], 0
	v_mov_b64_e32 v[58:59], 0
	v_mov_b64_e32 v[60:61], 0
	v_mov_b64_e32 v[62:63], 0
	v_mov_b64_e32 v[64:65], 0
	v_mov_b64_e32 v[66:67], 0
	v_mov_b64_e32 v[68:69], 0
	v_mov_b64_e32 v[70:71], 0
	v_mov_b64_e32 v[72:73], 0
	v_mov_b64_e32 v[74:75], 0
	v_mov_b64_e32 v[76:77], 0
	v_mov_b64_e32 v[78:79], 0
	v_mov_b64_e32 v[80:81], 0
	v_mov_b64_e32 v[82:83], 0
	v_mov_b64_e32 v[84:85], 0
	v_mov_b64_e32 v[86:87], 0
	v_mov_b64_e32 v[88:89], 0
	v_mov_b64_e32 v[90:91], 0
	v_mov_b64_e32 v[92:93], 0
	v_mov_b64_e32 v[94:95], 0
	v_mov_b64_e32 v[96:97], 0
	v_mov_b64_e32 v[98:99], 0
	v_mov_b64_e32 v[100:101], 0
	v_mov_b64_e32 v[102:103], 0
	v_mov_b64_e32 v[104:105], 0
	v_mov_b64_e32 v[106:107], 0
	v_mov_b64_e32 v[108:109], 0
	v_mov_b64_e32 v[110:111], 0
	v_mov_b64_e32 v[112:113], 0
	v_mov_b64_e32 v[114:115], 0
	v_mov_b64_e32 v[116:117], 0
	v_mov_b64_e32 v[118:119], 0
	v_mov_b64_e32 v[120:121], 0
	v_mov_b64_e32 v[122:123], 0
	v_mov_b64_e32 v[124:125], 0
	v_mov_b64_e32 v[126:127], 0
	s_addc_u32 s52, s21, 0
	s_mov_b32 s53, -2
